# on top of v35: nt hint also on F2 (Y) and M1 GEMM (QM/KN/VTM) epilogue stores
# baseline (speedup 1.0000x reference)
.LBB0_364:
	s_cmp_gt_i32 s6, 5
	s_cselect_b32 s6, s51, 0x37b00000
	s_cselect_b32 s27, 0x400, s50
	s_cselect_b32 s39, 8, 0
	s_add_u32 s34, s18, s6
	s_addc_u32 s35, s19, 0
	s_lshl_b32 s40, s56, 12
	v_add_u32_e32 v146, s40, v150
	v_or_b32_e32 v146, s39, v146
	v_ashrrev_i32_e32 v147, 31, v146
	v_lshl_add_u64 v[146:147], v[146:147], 2, s[2:3]
	global_load_dwordx4 v[162:165], v[146:147], off
	global_load_dwordx4 v[166:169], v[146:147], off offset:16
	global_load_dwordx4 v[170:173], v[146:147], off offset:1024
	global_load_dwordx4 v[174:177], v[146:147], off offset:1040
	global_load_dwordx4 v[178:181], v[146:147], off offset:2048
	global_load_dwordx4 v[182:185], v[146:147], off offset:2064
	global_load_dwordx4 v[186:189], v[146:147], off offset:3072
	global_load_dwordx4 v[190:193], v[146:147], off offset:3088
	v_mov_b64_e32 v[146:147], s[24:25]
	s_lshl_b32 s38, s56, 8
	s_lshl_b32 s6, s57, 8
	v_add_u32_e32 v194, s38, v148
	s_ashr_i32 s7, s6, 31
	v_mad_i64_i32 v[194:195], s[36:37], s27, v194, 0
	s_lshl_b64 s[36:37], s[6:7], 1
	v_lshl_add_u64 v[194:195], v[194:195], 1, s[34:35]
	v_add_u32_e32 v198, s38, v151
	s_waitcnt vmcnt(0)
	v_mov_b32_e32 v196, v162
	v_mov_b32_e32 v197, v166
	v_mov_b32_e32 v166, v163
	v_mov_b32_e32 v162, v164
	v_mov_b32_e32 v163, v168
	v_mov_b32_e32 v168, v165
	v_mov_b32_e32 v164, v170
	v_mov_b32_e32 v165, v174
	v_mov_b32_e32 v174, v171
	v_mov_b32_e32 v170, v172
	v_mov_b32_e32 v171, v176
	v_mov_b32_e32 v176, v173
	v_pk_add_f32 v[166:167], v[196:197], v[166:167]
	v_pk_add_f32 v[162:163], v[162:163], v[168:169]
	v_pk_add_f32 v[164:165], v[164:165], v[174:175]
	v_pk_add_f32 v[168:169], v[170:171], v[176:177]
	v_pk_add_f32 v[162:163], v[166:167], v[162:163]
	v_pk_add_f32 v[164:165], v[164:165], v[168:169]
	v_mov_b32_e32 v167, v162
	v_mov_b32_e32 v166, v164
	v_mov_b32_e32 v162, v165
	v_pk_add_f32 v[162:163], v[166:167], v[162:163]
	s_nop 0
	v_pk_fma_f32 v[162:163], v[162:163], s[22:23], v[146:147] op_sel_hi:[1,0,0]
	s_nop 0
	v_mul_f32_e32 v164, 0x4b800000, v163
	v_cmp_gt_f32_e32 vcc, s52, v163
	v_cmp_gt_f32_e64 s[6:7], s52, v162
	s_nop 0
	v_cndmask_b32_e32 v163, v163, v164, vcc
	v_rsq_f32_e32 v163, v163
	v_lshl_add_u64 v[164:165], v[194:195], 0, s[36:37]
	v_lshl_add_u64 v[164:165], v[164:165], 0, v[136:137]
	v_mul_f32_e32 v166, 0x45800000, v163
	v_cndmask_b32_e32 v166, v163, v166, vcc
	v_pk_mul_f32 v[126:127], v[126:127], v[166:167] op_sel_hi:[1,0]
	v_pk_mul_f32 v[124:125], v[124:125], v[166:167] op_sel_hi:[1,0]
	v_pk_mul_f32 v[168:169], v[122:123], v[166:167] op_sel_hi:[1,0]
	v_pk_mul_f32 v[122:123], v[120:121], v[166:167] op_sel_hi:[1,0]
	v_cvt_pk_bf16_f32 v120, v124, v125
	v_cvt_pk_bf16_f32 v121, v126, v127
	v_cvt_pk_bf16_f32 v122, v122, v123
	v_cvt_pk_bf16_f32 v123, v168, v169
	global_store_dwordx4 v[164:165], v[120:123], off nt
	v_pk_mul_f32 v[118:119], v[118:119], v[166:167] op_sel_hi:[1,0]
	v_pk_mul_f32 v[116:117], v[116:117], v[166:167] op_sel_hi:[1,0]
	v_pk_mul_f32 v[120:121], v[110:111], v[166:167] op_sel_hi:[1,0]
	v_pk_mul_f32 v[110:111], v[108:109], v[166:167] op_sel_hi:[1,0]
	v_cvt_pk_bf16_f32 v108, v116, v117
	v_cvt_pk_bf16_f32 v109, v118, v119
	v_cvt_pk_bf16_f32 v110, v110, v111
	v_cvt_pk_bf16_f32 v111, v120, v121
	global_store_dwordx4 v[164:165], v[108:111], off offset:256 nt
	s_nop 1
	v_mul_f32_e32 v108, 0x4b800000, v162
	v_cndmask_b32_e64 v108, v162, v108, s[6:7]
	v_rsq_f32_e32 v110, v108
	v_mad_i64_i32 v[108:109], s[56:57], s27, v198, 0
	v_lshl_add_u64 v[108:109], v[108:109], 1, s[34:35]
	v_mul_f32_e32 v111, 0x45800000, v110
	v_cndmask_b32_e64 v110, v110, v111, s[6:7]
	v_pk_mul_f32 v[114:115], v[114:115], v[110:111] op_sel_hi:[1,0]
	v_pk_mul_f32 v[112:113], v[112:113], v[110:111] op_sel_hi:[1,0]
	v_pk_mul_f32 v[116:117], v[106:107], v[110:111] op_sel_hi:[1,0]
	v_pk_mul_f32 v[106:107], v[104:105], v[110:111] op_sel_hi:[1,0]
	v_lshl_add_u64 v[108:109], v[108:109], 0, s[36:37]
	v_cvt_pk_bf16_f32 v104, v112, v113
	v_cvt_pk_bf16_f32 v105, v114, v115
	v_cvt_pk_bf16_f32 v106, v106, v107
	v_cvt_pk_bf16_f32 v107, v116, v117
	v_lshl_add_u64 v[108:109], v[108:109], 0, v[136:137]
	global_store_dwordx4 v[108:109], v[104:107], off nt
	v_pk_mul_f32 v[102:103], v[102:103], v[110:111] op_sel_hi:[1,0]
	v_pk_mul_f32 v[100:101], v[100:101], v[110:111] op_sel_hi:[1,0]
	v_pk_mul_f32 v[104:105], v[98:99], v[110:111] op_sel_hi:[1,0]
	v_pk_mul_f32 v[98:99], v[96:97], v[110:111] op_sel_hi:[1,0]
	v_cvt_pk_bf16_f32 v96, v100, v101
	v_cvt_pk_bf16_f32 v97, v102, v103
	v_cvt_pk_bf16_f32 v98, v98, v99
	v_cvt_pk_bf16_f32 v99, v104, v105
	global_store_dwordx4 v[108:109], v[96:99], off offset:256 nt
	s_nop 1
	v_mov_b32_e32 v96, v178
	v_mov_b32_e32 v97, v182
	v_mov_b32_e32 v182, v179
	v_mov_b32_e32 v98, v180
	v_mov_b32_e32 v99, v184
	v_mov_b32_e32 v184, v181
	v_add_u32_e32 v100, s38, v152
	v_pk_add_f32 v[96:97], v[96:97], v[182:183]
	v_pk_add_f32 v[98:99], v[98:99], v[184:185]
	v_mov_b32_e32 v101, v190
	v_pk_add_f32 v[96:97], v[96:97], v[98:99]
	v_mad_i64_i32 v[98:99], s[6:7], s27, v100, 0
	v_mov_b32_e32 v100, v186
	v_mov_b32_e32 v190, v187
	v_mov_b32_e32 v102, v188
	v_mov_b32_e32 v103, v192
	v_mov_b32_e32 v192, v189
	v_pk_add_f32 v[100:101], v[100:101], v[190:191]
	v_pk_add_f32 v[102:103], v[102:103], v[192:193]
	v_lshl_add_u64 v[98:99], v[98:99], 1, s[34:35]
	v_pk_add_f32 v[100:101], v[100:101], v[102:103]
	v_mov_b32_e32 v103, v96
	v_mov_b32_e32 v102, v100
	v_mov_b32_e32 v96, v101
	v_pk_add_f32 v[96:97], v[102:103], v[96:97]
	v_add_u32_e32 v101, s38, v153
	v_pk_fma_f32 v[96:97], v[96:97], s[22:23], v[146:147] op_sel_hi:[1,0,0]
	v_lshl_add_u64 v[98:99], v[98:99], 0, s[36:37]
	v_mul_f32_e32 v100, 0x4b800000, v97
	v_cmp_gt_f32_e32 vcc, s52, v97
	v_lshl_add_u64 v[98:99], v[98:99], 0, v[136:137]
	v_cmp_gt_f32_e64 s[6:7], s52, v96
	v_cndmask_b32_e32 v97, v97, v100, vcc
	v_rsq_f32_e32 v97, v97
	s_nop 0
	v_mul_f32_e32 v100, 0x45800000, v97
	v_cndmask_b32_e32 v100, v97, v100, vcc
	v_pk_mul_f32 v[94:95], v[94:95], v[100:101] op_sel_hi:[1,0]
	v_pk_mul_f32 v[92:93], v[92:93], v[100:101] op_sel_hi:[1,0]
	v_pk_mul_f32 v[102:103], v[90:91], v[100:101] op_sel_hi:[1,0]
	v_pk_mul_f32 v[90:91], v[88:89], v[100:101] op_sel_hi:[1,0]
	v_cvt_pk_bf16_f32 v88, v92, v93
	v_cvt_pk_bf16_f32 v89, v94, v95
	v_cvt_pk_bf16_f32 v90, v90, v91
	v_cvt_pk_bf16_f32 v91, v102, v103
	global_store_dwordx4 v[98:99], v[88:91], off nt
	v_pk_mul_f32 v[86:87], v[86:87], v[100:101] op_sel_hi:[1,0]
	v_pk_mul_f32 v[84:85], v[84:85], v[100:101] op_sel_hi:[1,0]
	v_pk_mul_f32 v[88:89], v[78:79], v[100:101] op_sel_hi:[1,0]
	v_pk_mul_f32 v[78:79], v[76:77], v[100:101] op_sel_hi:[1,0]
	v_cvt_pk_bf16_f32 v76, v84, v85
	v_cvt_pk_bf16_f32 v77, v86, v87
	v_cvt_pk_bf16_f32 v78, v78, v79
	v_cvt_pk_bf16_f32 v79, v88, v89
	global_store_dwordx4 v[98:99], v[76:79], off offset:256 nt
	s_nop 1
	v_mul_f32_e32 v76, 0x4b800000, v96
	v_cndmask_b32_e64 v76, v96, v76, s[6:7]
	v_rsq_f32_e32 v78, v76
	v_mad_i64_i32 v[76:77], s[56:57], s27, v101, 0
	v_lshl_add_u64 v[76:77], v[76:77], 1, s[34:35]
	v_mul_f32_e32 v79, 0x45800000, v78
	v_cndmask_b32_e64 v78, v78, v79, s[6:7]
	v_pk_mul_f32 v[82:83], v[82:83], v[78:79] op_sel_hi:[1,0]
	v_pk_mul_f32 v[80:81], v[80:81], v[78:79] op_sel_hi:[1,0]
	v_pk_mul_f32 v[84:85], v[74:75], v[78:79] op_sel_hi:[1,0]
	v_pk_mul_f32 v[74:75], v[72:73], v[78:79] op_sel_hi:[1,0]
	v_lshl_add_u64 v[76:77], v[76:77], 0, s[36:37]
	v_cvt_pk_bf16_f32 v72, v80, v81
	v_cvt_pk_bf16_f32 v73, v82, v83
	v_cvt_pk_bf16_f32 v74, v74, v75
	v_cvt_pk_bf16_f32 v75, v84, v85
	v_lshl_add_u64 v[76:77], v[76:77], 0, v[136:137]
	global_store_dwordx4 v[76:77], v[72:75], off nt
	v_pk_mul_f32 v[70:71], v[70:71], v[78:79] op_sel_hi:[1,0]
	v_pk_mul_f32 v[68:69], v[68:69], v[78:79] op_sel_hi:[1,0]
	v_pk_mul_f32 v[72:73], v[66:67], v[78:79] op_sel_hi:[1,0]
	v_pk_mul_f32 v[66:67], v[64:65], v[78:79] op_sel_hi:[1,0]
	v_cvt_pk_bf16_f32 v64, v68, v69
	v_cvt_pk_bf16_f32 v65, v70, v71
	v_cvt_pk_bf16_f32 v66, v66, v67
	v_cvt_pk_bf16_f32 v67, v72, v73
	global_store_dwordx4 v[76:77], v[64:67], off offset:256 nt
	s_nop 1
	v_or_b32_e32 v64, s39, v154
	v_add_u32_e32 v64, s40, v64
	v_ashrrev_i32_e32 v65, 31, v64
	v_lshl_add_u64 v[92:93], v[64:65], 2, s[2:3]
	global_load_dwordx4 v[64:67], v[92:93], off
	global_load_dwordx4 v[68:71], v[92:93], off offset:16
	global_load_dwordx4 v[72:75], v[92:93], off offset:1024
	global_load_dwordx4 v[76:79], v[92:93], off offset:1040
	global_load_dwordx4 v[80:83], v[92:93], off offset:2048
	global_load_dwordx4 v[84:87], v[92:93], off offset:2064
	global_load_dwordx4 v[88:91], v[92:93], off offset:3072
	s_nop 0
	global_load_dwordx4 v[92:95], v[92:93], off offset:3088
	v_add_u32_e32 v96, s38, v155
	v_mad_i64_i32 v[96:97], s[6:7], s27, v96, 0
	v_lshl_add_u64 v[96:97], v[96:97], 1, s[34:35]
	v_add_u32_e32 v100, s38, v156
	s_waitcnt vmcnt(7)
	v_mov_b32_e32 v98, v64
	s_waitcnt vmcnt(6)
	v_mov_b32_e32 v99, v68
	v_mov_b32_e32 v68, v65
	v_mov_b32_e32 v64, v66
	v_mov_b32_e32 v65, v70
	v_mov_b32_e32 v70, v67
	s_waitcnt vmcnt(5)
	v_mov_b32_e32 v66, v72
	s_waitcnt vmcnt(4)
	v_mov_b32_e32 v67, v76
	v_mov_b32_e32 v76, v73
	v_mov_b32_e32 v72, v74
	v_mov_b32_e32 v73, v78
	v_mov_b32_e32 v78, v75
	v_pk_add_f32 v[68:69], v[98:99], v[68:69]
	v_pk_add_f32 v[64:65], v[64:65], v[70:71]
	v_pk_add_f32 v[66:67], v[66:67], v[76:77]
	v_pk_add_f32 v[70:71], v[72:73], v[78:79]
	v_pk_add_f32 v[64:65], v[68:69], v[64:65]
	v_pk_add_f32 v[66:67], v[66:67], v[70:71]
	v_mov_b32_e32 v69, v64
	v_mov_b32_e32 v68, v66
	v_mov_b32_e32 v64, v67
	v_pk_add_f32 v[64:65], v[68:69], v[64:65]
	s_nop 0
	v_pk_fma_f32 v[64:65], v[64:65], s[22:23], v[146:147] op_sel_hi:[1,0,0]
	s_nop 0
	v_mul_f32_e32 v66, 0x4b800000, v65
	v_cmp_gt_f32_e32 vcc, s52, v65
	v_cmp_gt_f32_e64 s[6:7], s52, v64
	s_nop 0
	v_cndmask_b32_e32 v65, v65, v66, vcc
	v_rsq_f32_e32 v65, v65
	v_lshl_add_u64 v[66:67], v[96:97], 0, s[36:37]
	v_lshl_add_u64 v[66:67], v[66:67], 0, v[136:137]
	v_mul_f32_e32 v68, 0x45800000, v65
	v_cndmask_b32_e32 v68, v65, v68, vcc
	v_pk_mul_f32 v[62:63], v[62:63], v[68:69] op_sel_hi:[1,0]
	v_pk_mul_f32 v[60:61], v[60:61], v[68:69] op_sel_hi:[1,0]
	v_pk_mul_f32 v[70:71], v[58:59], v[68:69] op_sel_hi:[1,0]
	v_pk_mul_f32 v[58:59], v[56:57], v[68:69] op_sel_hi:[1,0]
	v_cvt_pk_bf16_f32 v56, v60, v61
	v_cvt_pk_bf16_f32 v57, v62, v63
	v_cvt_pk_bf16_f32 v58, v58, v59
	v_cvt_pk_bf16_f32 v59, v70, v71
	global_store_dwordx4 v[66:67], v[56:59], off nt
	v_pk_mul_f32 v[54:55], v[54:55], v[68:69] op_sel_hi:[1,0]
	v_pk_mul_f32 v[52:53], v[52:53], v[68:69] op_sel_hi:[1,0]
	v_pk_mul_f32 v[56:57], v[46:47], v[68:69] op_sel_hi:[1,0]
	v_pk_mul_f32 v[46:47], v[44:45], v[68:69] op_sel_hi:[1,0]
	v_cvt_pk_bf16_f32 v44, v52, v53
	v_cvt_pk_bf16_f32 v45, v54, v55
	v_cvt_pk_bf16_f32 v46, v46, v47
	v_cvt_pk_bf16_f32 v47, v56, v57
	global_store_dwordx4 v[66:67], v[44:47], off offset:256 nt
	s_nop 1
	v_mul_f32_e32 v44, 0x4b800000, v64
	v_cndmask_b32_e64 v44, v64, v44, s[6:7]
	v_rsq_f32_e32 v46, v44
	v_mad_i64_i32 v[44:45], s[40:41], s27, v100, 0
	v_lshl_add_u64 v[44:45], v[44:45], 1, s[34:35]
	v_mul_f32_e32 v47, 0x45800000, v46
	v_cndmask_b32_e64 v46, v46, v47, s[6:7]
	v_pk_mul_f32 v[50:51], v[50:51], v[46:47] op_sel_hi:[1,0]
	v_pk_mul_f32 v[48:49], v[48:49], v[46:47] op_sel_hi:[1,0]
	v_pk_mul_f32 v[52:53], v[42:43], v[46:47] op_sel_hi:[1,0]
	v_pk_mul_f32 v[42:43], v[40:41], v[46:47] op_sel_hi:[1,0]
	v_lshl_add_u64 v[44:45], v[44:45], 0, s[36:37]
	v_cvt_pk_bf16_f32 v40, v48, v49
	v_cvt_pk_bf16_f32 v41, v50, v51
	v_cvt_pk_bf16_f32 v42, v42, v43
	v_cvt_pk_bf16_f32 v43, v52, v53
	v_lshl_add_u64 v[44:45], v[44:45], 0, v[136:137]
	global_store_dwordx4 v[44:45], v[40:43], off nt
	v_pk_mul_f32 v[38:39], v[38:39], v[46:47] op_sel_hi:[1,0]
	v_pk_mul_f32 v[36:37], v[36:37], v[46:47] op_sel_hi:[1,0]
	v_pk_mul_f32 v[40:41], v[34:35], v[46:47] op_sel_hi:[1,0]
	v_pk_mul_f32 v[34:35], v[32:33], v[46:47] op_sel_hi:[1,0]
	v_cvt_pk_bf16_f32 v32, v36, v37
	v_cvt_pk_bf16_f32 v33, v38, v39
	v_cvt_pk_bf16_f32 v34, v34, v35
	v_cvt_pk_bf16_f32 v35, v40, v41
	global_store_dwordx4 v[44:45], v[32:35], off offset:256 nt
	s_waitcnt vmcnt(7)
	s_nop 0
	v_mov_b32_e32 v32, v80
	s_waitcnt vmcnt(6)
	v_mov_b32_e32 v33, v84
	v_mov_b32_e32 v84, v81
	v_mov_b32_e32 v34, v82
	v_mov_b32_e32 v35, v86
	v_mov_b32_e32 v86, v83
	v_add_u32_e32 v36, s38, v157
	v_pk_add_f32 v[32:33], v[32:33], v[84:85]
	v_pk_add_f32 v[34:35], v[34:35], v[86:87]
	s_waitcnt vmcnt(4)
	v_mov_b32_e32 v37, v92
	v_pk_add_f32 v[32:33], v[32:33], v[34:35]
	v_mad_i64_i32 v[34:35], s[6:7], s27, v36, 0
	v_mov_b32_e32 v36, v88
	v_mov_b32_e32 v92, v89
	v_mov_b32_e32 v38, v90
	v_mov_b32_e32 v39, v94
	v_mov_b32_e32 v94, v91
	v_pk_add_f32 v[36:37], v[36:37], v[92:93]
	v_pk_add_f32 v[38:39], v[38:39], v[94:95]
	v_lshl_add_u64 v[34:35], v[34:35], 1, s[34:35]
	v_pk_add_f32 v[36:37], v[36:37], v[38:39]
	v_mov_b32_e32 v39, v32
	v_mov_b32_e32 v38, v36
	v_mov_b32_e32 v32, v37
	v_pk_add_f32 v[32:33], v[38:39], v[32:33]
	v_add_u32_e32 v37, s38, v158
	v_pk_fma_f32 v[32:33], v[32:33], s[22:23], v[146:147] op_sel_hi:[1,0,0]
	v_lshl_add_u64 v[34:35], v[34:35], 0, s[36:37]
	v_mul_f32_e32 v36, 0x4b800000, v33
	v_cmp_gt_f32_e32 vcc, s52, v33
	v_lshl_add_u64 v[34:35], v[34:35], 0, v[136:137]
	v_cmp_gt_f32_e64 s[6:7], s52, v32
	v_cndmask_b32_e32 v33, v33, v36, vcc
	v_rsq_f32_e32 v33, v33
	s_nop 0
	v_mul_f32_e32 v36, 0x45800000, v33
	v_cndmask_b32_e32 v36, v33, v36, vcc
	v_pk_mul_f32 v[30:31], v[30:31], v[36:37] op_sel_hi:[1,0]
	v_pk_mul_f32 v[28:29], v[28:29], v[36:37] op_sel_hi:[1,0]
	v_pk_mul_f32 v[38:39], v[26:27], v[36:37] op_sel_hi:[1,0]
	v_pk_mul_f32 v[26:27], v[24:25], v[36:37] op_sel_hi:[1,0]
	v_cvt_pk_bf16_f32 v24, v28, v29
	v_cvt_pk_bf16_f32 v25, v30, v31
	v_cvt_pk_bf16_f32 v26, v26, v27
	v_cvt_pk_bf16_f32 v27, v38, v39
	global_store_dwordx4 v[34:35], v[24:27], off nt
	v_pk_mul_f32 v[22:23], v[22:23], v[36:37] op_sel_hi:[1,0]
	v_pk_mul_f32 v[20:21], v[20:21], v[36:37] op_sel_hi:[1,0]
	v_pk_mul_f32 v[24:25], v[14:15], v[36:37] op_sel_hi:[1,0]
	v_pk_mul_f32 v[14:15], v[12:13], v[36:37] op_sel_hi:[1,0]
	v_cvt_pk_bf16_f32 v12, v20, v21
	v_cvt_pk_bf16_f32 v13, v22, v23
	v_cvt_pk_bf16_f32 v14, v14, v15
	v_cvt_pk_bf16_f32 v15, v24, v25
	global_store_dwordx4 v[34:35], v[12:15], off offset:256 nt
	s_nop 1
	v_mul_f32_e32 v12, 0x4b800000, v32
	v_cndmask_b32_e64 v12, v32, v12, s[6:7]
	v_rsq_f32_e32 v14, v12
	v_mad_i64_i32 v[12:13], s[38:39], s27, v37, 0
	v_lshl_add_u64 v[12:13], v[12:13], 1, s[34:35]
	v_mul_f32_e32 v15, 0x45800000, v14
	v_cndmask_b32_e64 v14, v14, v15, s[6:7]
	v_pk_mul_f32 v[18:19], v[18:19], v[14:15] op_sel_hi:[1,0]
	v_pk_mul_f32 v[16:17], v[16:17], v[14:15] op_sel_hi:[1,0]
	v_pk_mul_f32 v[20:21], v[10:11], v[14:15] op_sel_hi:[1,0]
	v_pk_mul_f32 v[10:11], v[8:9], v[14:15] op_sel_hi:[1,0]
	v_lshl_add_u64 v[12:13], v[12:13], 0, s[36:37]
	v_cvt_pk_bf16_f32 v8, v16, v17
	v_cvt_pk_bf16_f32 v9, v18, v19
	v_cvt_pk_bf16_f32 v10, v10, v11
	v_cvt_pk_bf16_f32 v11, v20, v21
	v_lshl_add_u64 v[12:13], v[12:13], 0, v[136:137]
	global_store_dwordx4 v[12:13], v[8:11], off nt
	v_pk_mul_f32 v[6:7], v[6:7], v[14:15] op_sel_hi:[1,0]
	v_pk_mul_f32 v[4:5], v[4:5], v[14:15] op_sel_hi:[1,0]
	v_pk_mul_f32 v[8:9], v[2:3], v[14:15] op_sel_hi:[1,0]
	v_pk_mul_f32 v[2:3], v[0:1], v[14:15] op_sel_hi:[1,0]
	v_cvt_pk_bf16_f32 v0, v4, v5
	v_cvt_pk_bf16_f32 v1, v6, v7
	v_cvt_pk_bf16_f32 v2, v2, v3
	v_cvt_pk_bf16_f32 v3, v8, v9
	global_store_dwordx4 v[12:13], v[0:3], off offset:256 nt
	s_andn2_b64 vcc, exec, s[4:5]
	s_mov_b64 s[4:5], -1
	s_cbranch_vccnz .LBB0_353
	s_andn2_b64 vcc, exec, s[10:11]
	s_cbranch_vccnz .LBB0_352
	s_barrier
	s_branch .LBB0_352

.LBB0_380:
	s_lshl_b32 s8, s50, 8
	v_or_b32_e32 v162, s8, v156
	v_lshlrev_b32_e32 v146, 4, v162
	v_ashrrev_i32_e32 v147, 31, v146
	v_lshl_add_u64 v[148:149], v[146:147], 2, s[2:3]
	global_load_dwordx4 v[164:167], v[148:149], off offset:32
	global_load_dwordx4 v[168:171], v[148:149], off offset:96
	global_load_dwordx4 v[172:175], v[148:149], off offset:48
	global_load_dwordx4 v[176:179], v[148:149], off offset:112
	global_load_dwordx4 v[180:183], v[148:149], off offset:160
	global_load_dwordx4 v[184:187], v[148:149], off offset:224
	global_load_dwordx4 v[188:191], v[148:149], off offset:176
	global_load_dwordx4 v[192:195], v[148:149], off offset:240
	global_load_dwordx4 v[196:199], v[148:149], off offset:288
	global_load_dwordx4 v[200:203], v[148:149], off offset:352
	global_load_dwordx4 v[204:207], v[148:149], off offset:304
	global_load_dwordx4 v[208:211], v[148:149], off offset:368
	global_load_dwordx4 v[212:215], v[148:149], off offset:432
	global_load_dwordx4 v[218:221], v[148:149], off offset:416
	global_load_dwordx4 v[222:225], v[148:149], off offset:496
	global_load_dwordx4 v[226:229], v[148:149], off offset:480
	s_ashr_i32 s6, s50, 4
	v_mov_b64_e32 v[146:147], s[26:27]
	s_ashr_i32 s7, s6, 31
	v_lshl_add_u32 v150, s51, 8, v154
	s_lshl_b64 s[50:51], s[6:7], 23
	v_bitop3_b32 v136, s8, v160, v156 bitop3:0xc8
	v_lshlrev_b32_e32 v136, 1, v136
	s_waitcnt vmcnt(0)
	v_mov_b32_e32 v152, v164
	v_mov_b32_e32 v153, v168
	v_mov_b32_e32 v168, v165
	v_mov_b32_e32 v164, v166
	v_mov_b32_e32 v165, v170
	v_mov_b32_e32 v170, v167
	v_mov_b32_e32 v166, v172
	v_mov_b32_e32 v167, v176
	v_mov_b32_e32 v176, v173
	v_mov_b32_e32 v172, v174
	v_mov_b32_e32 v173, v178
	v_mov_b32_e32 v178, v175
	v_mov_b32_e32 v174, v180
	v_mov_b32_e32 v175, v184
	v_mov_b32_e32 v184, v181
	v_mov_b32_e32 v180, v182
	v_mov_b32_e32 v181, v186
	v_mov_b32_e32 v186, v183
	v_mov_b32_e32 v182, v188
	v_mov_b32_e32 v183, v192
	v_mov_b32_e32 v192, v189
	v_mov_b32_e32 v188, v190
	v_mov_b32_e32 v189, v194
	v_mov_b32_e32 v194, v191
	v_pk_add_f32 v[152:153], v[152:153], v[168:169]
	v_pk_add_f32 v[164:165], v[164:165], v[170:171]
	v_pk_add_f32 v[166:167], v[166:167], v[176:177]
	v_pk_add_f32 v[168:169], v[172:173], v[178:179]
	v_pk_add_f32 v[170:171], v[174:175], v[184:185]
	v_pk_add_f32 v[172:173], v[180:181], v[186:187]
	v_pk_add_f32 v[174:175], v[182:183], v[192:193]
	v_pk_add_f32 v[176:177], v[188:189], v[194:195]
	v_pk_add_f32 v[152:153], v[152:153], v[164:165]
	v_pk_add_f32 v[164:165], v[166:167], v[168:169]
	v_pk_add_f32 v[166:167], v[170:171], v[172:173]
	v_pk_add_f32 v[168:169], v[174:175], v[176:177]
	v_pk_add_f32 v[152:153], v[152:153], v[164:165]
	v_pk_add_f32 v[164:165], v[166:167], v[168:169]
	v_pk_fma_f32 v[152:153], v[152:153], s[24:25], v[146:147] op_sel_hi:[1,0,0]
	v_pk_fma_f32 v[164:165], v[164:165], s[24:25], v[146:147] op_sel_hi:[1,0,0]
	v_mul_f32_e32 v151, 0x4b800000, v152
	v_mul_f32_e32 v163, 0x4b800000, v153
	v_cmp_gt_f32_e32 vcc, s66, v152
	v_cmp_gt_f32_e64 s[6:7], s66, v153
	v_mul_f32_e32 v166, 0x4b800000, v164
	v_mul_f32_e32 v167, 0x4b800000, v165
	v_cndmask_b32_e32 v151, v152, v151, vcc
	v_cndmask_b32_e64 v153, v153, v163, s[6:7]
	v_cmp_gt_f32_e64 s[8:9], s66, v164
	v_cmp_gt_f32_e64 s[10:11], s66, v165
	v_rsq_f32_e32 v152, v151
	v_cndmask_b32_e64 v163, v164, v166, s[8:9]
	v_cndmask_b32_e64 v165, v165, v167, s[10:11]
	v_rsq_f32_e32 v153, v153
	v_rsq_f32_e32 v164, v163
	v_rsq_f32_e32 v165, v165
	v_mov_b32_e32 v190, v196
	v_mov_b32_e32 v191, v200
	v_mov_b32_e32 v200, v197
	v_mov_b32_e32 v196, v198
	v_mov_b32_e32 v197, v202
	v_mov_b32_e32 v202, v199
	v_mov_b32_e32 v198, v204
	v_mov_b32_e32 v199, v208
	v_pk_mul_f32 v[168:169], v[152:153], s[28:29] op_sel_hi:[1,0]
	v_mov_b32_e32 v208, v205
	v_mov_b32_e32 v172, v206
	v_mov_b32_e32 v173, v210
	v_mov_b32_e32 v210, v207
	v_pk_add_f32 v[178:179], v[190:191], v[200:201]
	v_pk_add_f32 v[166:167], v[196:197], v[202:203]
	v_pk_mul_f32 v[170:171], v[164:165], s[28:29] op_sel_hi:[1,0]
	v_cndmask_b32_e64 v153, v153, v169, s[6:7]
	v_cndmask_b32_e32 v152, v152, v168, vcc
	v_pk_add_f32 v[168:169], v[198:199], v[208:209]
	v_pk_add_f32 v[172:173], v[172:173], v[210:211]
	v_pk_add_f32 v[166:167], v[178:179], v[166:167]
	v_pk_add_f32 v[168:169], v[168:169], v[172:173]
	v_cndmask_b32_e64 v165, v165, v171, s[10:11]
	v_cndmask_b32_e64 v164, v164, v170, s[8:9]
	v_mov_b32_e32 v170, v218
	v_mov_b32_e32 v171, v226
	v_mov_b32_e32 v226, v219
	v_mov_b32_e32 v172, v220
	v_mov_b32_e32 v173, v228
	v_mov_b32_e32 v228, v221
	v_pk_add_f32 v[166:167], v[166:167], v[168:169]
	v_pk_add_f32 v[170:171], v[170:171], v[226:227]
	v_pk_add_f32 v[172:173], v[172:173], v[228:229]
	v_pk_fma_f32 v[166:167], v[166:167], s[24:25], v[146:147] op_sel_hi:[1,0,0]
	v_pk_add_f32 v[170:171], v[170:171], v[172:173]
	v_mov_b32_e32 v172, v212
	v_mov_b32_e32 v173, v222
	v_mov_b32_e32 v222, v213
	v_mov_b32_e32 v174, v214
	v_mov_b32_e32 v175, v224
	v_mov_b32_e32 v224, v215
	v_mul_f32_e32 v151, 0x4b800000, v166
	v_cmp_gt_f32_e32 vcc, s66, v166
	v_pk_add_f32 v[172:173], v[172:173], v[222:223]
	v_pk_add_f32 v[174:175], v[174:175], v[224:225]
	v_cndmask_b32_e32 v151, v166, v151, vcc
	v_pk_add_f32 v[172:173], v[172:173], v[174:175]
	v_rsq_f32_e32 v166, v151
	v_mul_f32_e32 v151, 0x4b800000, v167
	v_cmp_gt_f32_e64 s[6:7], s66, v167
	v_pk_add_f32 v[170:171], v[170:171], v[172:173]
	v_pk_mul_f32 v[124:125], v[124:125], v[152:153]
	v_cndmask_b32_e64 v151, v167, v151, s[6:7]
	v_pk_fma_f32 v[170:171], v[170:171], s[24:25], v[146:147] op_sel_hi:[1,0,0]
	v_rsq_f32_e32 v167, v151
	v_mul_f32_e32 v151, 0x4b800000, v170
	v_cmp_gt_f32_e64 s[8:9], s66, v170
	v_cmp_gt_f32_e64 s[10:11], s66, v171
	v_pk_mul_f32 v[168:169], v[166:167], s[28:29] op_sel_hi:[1,0]
	v_cndmask_b32_e64 v151, v170, v151, s[8:9]
	v_rsq_f32_e32 v170, v151
	v_mul_f32_e32 v151, 0x4b800000, v171
	v_cndmask_b32_e64 v151, v171, v151, s[10:11]
	v_rsq_f32_e32 v171, v151
	v_cndmask_b32_e64 v167, v167, v169, s[6:7]
	v_cndmask_b32_e32 v166, v166, v168, vcc
	v_pk_mul_f32 v[120:121], v[120:121], v[166:167]
	v_pk_mul_f32 v[168:169], v[170:171], s[28:29] op_sel_hi:[1,0]
	v_ashrrev_i32_e32 v151, 31, v150
	v_cndmask_b32_e64 v169, v171, v169, s[10:11]
	v_cndmask_b32_e64 v168, v170, v168, s[8:9]
	s_add_u32 s6, s59, s50
	v_pk_mul_f32 v[170:171], v[122:123], v[168:169]
	v_cvt_pk_bf16_f32 v122, v124, v125
	v_cvt_pk_bf16_f32 v124, v120, v121
	s_addc_u32 s7, s60, s51
	v_lshlrev_b64 v[120:121], 13, v[150:151]
	v_pk_mul_f32 v[126:127], v[126:127], v[164:165]
	v_lshl_add_u64 v[120:121], s[6:7], 0, v[120:121]
	v_cvt_pk_bf16_f32 v123, v126, v127
	v_cvt_pk_bf16_f32 v125, v170, v171
	v_lshl_add_u64 v[126:127], v[120:121], 0, v[136:137]
	global_store_dwordx4 v[126:127], v[122:125], off nt
	s_nop 1
	v_or_b32_e32 v122, 16, v150
	v_pk_mul_f32 v[116:117], v[116:117], v[152:153]
	v_pk_mul_f32 v[112:113], v[112:113], v[166:167]
	v_ashrrev_i32_e32 v123, 31, v122
	v_pk_mul_f32 v[124:125], v[114:115], v[168:169]
	v_cvt_pk_bf16_f32 v114, v116, v117
	v_cvt_pk_bf16_f32 v116, v112, v113
	v_lshlrev_b64 v[112:113], 13, v[122:123]
	v_pk_mul_f32 v[118:119], v[118:119], v[164:165]
	v_lshl_add_u64 v[112:113], s[6:7], 0, v[112:113]
	v_cvt_pk_bf16_f32 v115, v118, v119
	v_cvt_pk_bf16_f32 v117, v124, v125
	v_lshl_add_u64 v[118:119], v[112:113], 0, v[136:137]
	global_store_dwordx4 v[118:119], v[114:117], off nt
	s_nop 1
	v_or_b32_e32 v114, 32, v150
	v_pk_mul_f32 v[108:109], v[108:109], v[152:153]
	v_pk_mul_f32 v[104:105], v[104:105], v[166:167]
	v_ashrrev_i32_e32 v115, 31, v114
	v_pk_mul_f32 v[116:117], v[106:107], v[168:169]
	v_cvt_pk_bf16_f32 v106, v108, v109
	v_cvt_pk_bf16_f32 v108, v104, v105
	v_lshlrev_b64 v[104:105], 13, v[114:115]
	v_pk_mul_f32 v[110:111], v[110:111], v[164:165]
	v_lshl_add_u64 v[104:105], s[6:7], 0, v[104:105]
	v_cvt_pk_bf16_f32 v107, v110, v111
	v_cvt_pk_bf16_f32 v109, v116, v117
	v_lshl_add_u64 v[110:111], v[104:105], 0, v[136:137]
	global_store_dwordx4 v[110:111], v[106:109], off nt
	s_nop 1
	v_or_b32_e32 v106, 48, v150
	v_pk_mul_f32 v[100:101], v[100:101], v[152:153]
	v_pk_mul_f32 v[96:97], v[96:97], v[166:167]
	v_ashrrev_i32_e32 v107, 31, v106
	v_pk_mul_f32 v[108:109], v[98:99], v[168:169]
	v_cvt_pk_bf16_f32 v98, v100, v101
	v_cvt_pk_bf16_f32 v100, v96, v97
	v_lshlrev_b64 v[96:97], 13, v[106:107]
	v_pk_mul_f32 v[102:103], v[102:103], v[164:165]
	v_lshl_add_u64 v[96:97], s[6:7], 0, v[96:97]
	v_cvt_pk_bf16_f32 v99, v102, v103
	v_cvt_pk_bf16_f32 v101, v108, v109
	v_lshl_add_u64 v[102:103], v[96:97], 0, v[136:137]
	global_store_dwordx4 v[102:103], v[98:101], off nt
	s_nop 1
	v_add_u32_e32 v98, 0x80, v150
	v_pk_mul_f32 v[92:93], v[92:93], v[152:153]
	v_pk_mul_f32 v[88:89], v[88:89], v[166:167]
	v_ashrrev_i32_e32 v99, 31, v98
	v_pk_mul_f32 v[100:101], v[90:91], v[168:169]
	v_cvt_pk_bf16_f32 v90, v92, v93
	v_cvt_pk_bf16_f32 v92, v88, v89
	v_lshlrev_b64 v[88:89], 13, v[98:99]
	v_pk_mul_f32 v[94:95], v[94:95], v[164:165]
	v_lshl_add_u64 v[88:89], s[6:7], 0, v[88:89]
	v_cvt_pk_bf16_f32 v91, v94, v95
	v_cvt_pk_bf16_f32 v93, v100, v101
	v_lshl_add_u64 v[94:95], v[88:89], 0, v[136:137]
	global_store_dwordx4 v[94:95], v[90:93], off nt
	s_nop 1
	v_add_u32_e32 v90, 0x90, v150
	v_pk_mul_f32 v[84:85], v[84:85], v[152:153]
	v_pk_mul_f32 v[80:81], v[80:81], v[166:167]
	v_ashrrev_i32_e32 v91, 31, v90
	v_pk_mul_f32 v[92:93], v[82:83], v[168:169]
	v_cvt_pk_bf16_f32 v82, v84, v85
	v_cvt_pk_bf16_f32 v84, v80, v81
	v_lshlrev_b64 v[80:81], 13, v[90:91]
	v_pk_mul_f32 v[86:87], v[86:87], v[164:165]
	v_lshl_add_u64 v[80:81], s[6:7], 0, v[80:81]
	v_cvt_pk_bf16_f32 v83, v86, v87
	v_cvt_pk_bf16_f32 v85, v92, v93
	v_lshl_add_u64 v[86:87], v[80:81], 0, v[136:137]
	global_store_dwordx4 v[86:87], v[82:85], off nt
	s_nop 1
	v_add_u32_e32 v82, 0xa0, v150
	v_pk_mul_f32 v[76:77], v[76:77], v[152:153]
	v_pk_mul_f32 v[72:73], v[72:73], v[166:167]
	v_ashrrev_i32_e32 v83, 31, v82
	v_pk_mul_f32 v[84:85], v[74:75], v[168:169]
	v_cvt_pk_bf16_f32 v74, v76, v77
	v_cvt_pk_bf16_f32 v76, v72, v73
	v_lshlrev_b64 v[72:73], 13, v[82:83]
	v_pk_mul_f32 v[78:79], v[78:79], v[164:165]
	v_lshl_add_u64 v[72:73], s[6:7], 0, v[72:73]
	v_cvt_pk_bf16_f32 v75, v78, v79
	v_cvt_pk_bf16_f32 v77, v84, v85
	v_lshl_add_u64 v[78:79], v[72:73], 0, v[136:137]
	global_store_dwordx4 v[78:79], v[74:77], off nt
	s_nop 1
	v_add_u32_e32 v74, 0xb0, v150
	v_pk_mul_f32 v[68:69], v[68:69], v[152:153]
	v_pk_mul_f32 v[64:65], v[64:65], v[166:167]
	v_ashrrev_i32_e32 v75, 31, v74
	v_pk_mul_f32 v[76:77], v[66:67], v[168:169]
	v_cvt_pk_bf16_f32 v66, v68, v69
	v_cvt_pk_bf16_f32 v68, v64, v65
	v_lshlrev_b64 v[64:65], 13, v[74:75]
	v_pk_mul_f32 v[70:71], v[70:71], v[164:165]
	v_lshl_add_u64 v[64:65], s[6:7], 0, v[64:65]
	v_cvt_pk_bf16_f32 v67, v70, v71
	v_cvt_pk_bf16_f32 v69, v76, v77
	v_lshl_add_u64 v[70:71], v[64:65], 0, v[136:137]
	global_store_dwordx4 v[70:71], v[66:69], off nt
	v_add_co_u32_e32 v70, vcc, s57, v148
	v_lshl_add_u64 v[74:75], v[148:149], 0, s[30:31]
	s_nop 0
	v_addc_co_u32_e32 v71, vcc, 0, v149, vcc
	v_lshl_add_u64 v[78:79], v[148:149], 0, s[34:35]
	global_load_dwordx4 v[66:69], v[70:71], off offset:96
	s_nop 0
	global_load_dwordx4 v[74:77], v[74:75], off offset:16
	s_nop 0
	global_load_dwordx4 v[82:85], v[70:71], off offset:160
	global_load_dwordx4 v[90:93], v[70:71], off offset:224
	v_lshl_add_u64 v[86:87], v[148:149], 0, s[36:37]
	global_load_dwordx4 v[98:101], v[78:79], off offset:16
	global_load_dwordx4 v[106:109], v[86:87], off offset:16
	global_load_dwordx4 v[114:117], v[70:71], off offset:288
	global_load_dwordx4 v[122:125], v[70:71], off offset:352
	v_or_b32_e32 v78, 0x80, v162
	v_lshlrev_b32_e32 v78, 4, v78
	v_ashrrev_i32_e32 v79, 31, v78
	v_lshl_add_u64 v[78:79], v[78:79], 2, s[2:3]
	global_load_dwordx4 v[150:153], v[78:79], off offset:32
	global_load_dwordx4 v[164:167], v[78:79], off offset:48
	v_lshl_add_u64 v[78:79], v[148:149], 0, s[38:39]
	v_lshl_add_u64 v[86:87], v[148:149], 0, s[40:41]
	global_load_dwordx4 v[168:171], v[78:79], off offset:16
	global_load_dwordx4 v[172:175], v[86:87], off offset:16
	v_lshl_add_u64 v[78:79], v[148:149], 0, s[42:43]
	v_lshl_add_u64 v[86:87], v[148:149], 0, s[44:45]
	global_load_dwordx4 v[176:179], v[70:71], off offset:416
	global_load_dwordx4 v[180:183], v[70:71], off offset:480
	global_load_dwordx4 v[184:187], v[78:79], off offset:16
	global_load_dwordx4 v[188:191], v[86:87], off offset:16
	v_bitop3_b32 v110, v162, s67, v161 bitop3:0xc8
	v_lshlrev_b32_e32 v136, 1, v110
	s_waitcnt vmcnt(14)
	v_mov_b32_e32 v87, v74
	s_waitcnt vmcnt(13)
	v_mov_b32_e32 v102, v82
	s_waitcnt vmcnt(12)
	v_mov_b32_e32 v103, v90
	v_mov_b32_e32 v90, v83
	v_mov_b32_e32 v82, v84
	v_mov_b32_e32 v83, v92
	v_mov_b32_e32 v92, v85
	s_waitcnt vmcnt(11)
	v_mov_b32_e32 v84, v98
	s_waitcnt vmcnt(10)
	v_mov_b32_e32 v85, v106
	v_mov_b32_e32 v106, v99
	v_mov_b32_e32 v98, v100
	v_mov_b32_e32 v99, v108
	v_mov_b32_e32 v108, v101
	v_mov_b32_e32 v71, v66
	v_mov_b32_e32 v79, v68
	v_mov_b32_e32 v95, v76
	v_pk_add_f32 v[90:91], v[102:103], v[90:91]
	v_pk_add_f32 v[82:83], v[82:83], v[92:93]
	v_pk_add_f32 v[84:85], v[84:85], v[106:107]
	v_pk_add_f32 v[92:93], v[98:99], v[108:109]
	s_waitcnt vmcnt(7)
	v_mov_b32_e32 v70, v150
	v_mov_b32_e32 v66, v151
	v_mov_b32_e32 v78, v152
	v_mov_b32_e32 v68, v153
	s_waitcnt vmcnt(6)
	v_mov_b32_e32 v86, v164
	v_mov_b32_e32 v74, v165
	v_mov_b32_e32 v94, v166
	v_mov_b32_e32 v76, v167
	v_pk_add_f32 v[82:83], v[90:91], v[82:83]
	v_pk_add_f32 v[84:85], v[84:85], v[92:93]
	v_pk_add_f32 v[66:67], v[70:71], v[66:67]
	v_pk_add_f32 v[68:69], v[78:79], v[68:69]
	v_pk_add_f32 v[70:71], v[86:87], v[74:75]
	v_pk_add_f32 v[74:75], v[94:95], v[76:77]
	v_pk_add_f32 v[82:83], v[82:83], v[84:85]
	v_pk_add_f32 v[66:67], v[66:67], v[68:69]
	v_pk_add_f32 v[68:69], v[70:71], v[74:75]
	v_pk_fma_f32 v[76:77], v[82:83], s[24:25], v[146:147] op_sel_hi:[1,0,0]
	v_pk_add_f32 v[66:67], v[66:67], v[68:69]
	v_mul_f32_e32 v70, 0x4b800000, v76
	v_mul_f32_e32 v71, 0x4b800000, v77
	v_cmp_gt_f32_e32 vcc, s66, v76
	v_cmp_gt_f32_e64 s[6:7], s66, v77
	v_pk_fma_f32 v[66:67], v[66:67], s[24:25], v[146:147] op_sel_hi:[1,0,0]
	v_cndmask_b32_e32 v68, v76, v70, vcc
	v_cndmask_b32_e64 v69, v77, v71, s[6:7]
	v_mul_f32_e32 v70, 0x4b800000, v66
	v_mul_f32_e32 v71, 0x4b800000, v67
	v_cmp_gt_f32_e64 s[8:9], s66, v66
	v_cmp_gt_f32_e64 s[10:11], s66, v67
	v_rsq_f32_e32 v68, v68
	v_cndmask_b32_e64 v66, v66, v70, s[8:9]
	v_cndmask_b32_e64 v67, v67, v71, s[10:11]
	v_rsq_f32_e32 v66, v66
	v_rsq_f32_e32 v67, v67
	v_rsq_f32_e32 v69, v69
	v_mov_b32_e32 v100, v114
	v_mov_b32_e32 v101, v122
	v_mov_b32_e32 v122, v115
	v_mov_b32_e32 v70, v116
	v_mov_b32_e32 v71, v124
	v_mov_b32_e32 v124, v117
	v_pk_add_f32 v[74:75], v[100:101], v[122:123]
	v_pk_mul_f32 v[78:79], v[66:67], s[28:29] op_sel_hi:[1,0]
	v_pk_add_f32 v[70:71], v[70:71], v[124:125]
	v_cndmask_b32_e64 v67, v67, v79, s[10:11]
	v_cndmask_b32_e64 v66, v66, v78, s[8:9]
	v_pk_add_f32 v[70:71], v[74:75], v[70:71]
	s_waitcnt vmcnt(5)
	v_mov_b32_e32 v74, v168
	s_waitcnt vmcnt(4)
	v_mov_b32_e32 v75, v172
	v_mov_b32_e32 v172, v169
	v_mov_b32_e32 v78, v170
	v_mov_b32_e32 v79, v174
	v_mov_b32_e32 v174, v171
	v_pk_mul_f32 v[76:77], v[68:69], s[28:29] op_sel_hi:[1,0]
	v_pk_add_f32 v[74:75], v[74:75], v[172:173]
	v_pk_add_f32 v[78:79], v[78:79], v[174:175]
	v_cndmask_b32_e64 v69, v69, v77, s[6:7]
	v_pk_add_f32 v[74:75], v[74:75], v[78:79]
	v_cndmask_b32_e32 v68, v68, v76, vcc
	s_waitcnt vmcnt(3)
	v_mov_b32_e32 v76, v176
	s_waitcnt vmcnt(2)
	v_mov_b32_e32 v77, v180
	v_mov_b32_e32 v180, v177
	v_mov_b32_e32 v78, v178
	v_mov_b32_e32 v79, v182
	v_mov_b32_e32 v182, v179
	v_pk_add_f32 v[76:77], v[76:77], v[180:181]
	v_pk_add_f32 v[78:79], v[78:79], v[182:183]
	s_waitcnt vmcnt(1)
	v_mov_b32_e32 v82, v186
	v_pk_add_f32 v[76:77], v[76:77], v[78:79]
	v_mov_b32_e32 v78, v184
	s_waitcnt vmcnt(0)
	v_mov_b32_e32 v79, v188
	v_mov_b32_e32 v188, v185
	v_mov_b32_e32 v83, v190
	v_mov_b32_e32 v190, v187
	v_pk_add_f32 v[70:71], v[70:71], v[74:75]
	v_pk_add_f32 v[78:79], v[78:79], v[188:189]
	v_pk_add_f32 v[82:83], v[82:83], v[190:191]
	v_pk_fma_f32 v[70:71], v[70:71], s[24:25], v[146:147] op_sel_hi:[1,0,0]
	v_pk_add_f32 v[78:79], v[78:79], v[82:83]
	v_mul_f32_e32 v74, 0x4b800000, v70
	v_cmp_gt_f32_e64 s[8:9], s66, v70
	v_pk_add_f32 v[76:77], v[76:77], v[78:79]
	v_cmp_gt_f32_e64 s[10:11], s66, v71
	v_cndmask_b32_e64 v70, v70, v74, s[8:9]
	v_mul_f32_e32 v74, 0x4b800000, v71
	v_pk_fma_f32 v[76:77], v[76:77], s[24:25], v[146:147] op_sel_hi:[1,0,0]
	v_cndmask_b32_e64 v71, v71, v74, s[10:11]
	v_mul_f32_e32 v78, 0x4b800000, v76
	v_cmp_gt_f32_e32 vcc, s66, v76
	v_rsq_f32_e32 v70, v70
	v_rsq_f32_e32 v71, v71
	v_cndmask_b32_e32 v76, v76, v78, vcc
	v_mul_f32_e32 v78, 0x4b800000, v77
	v_cmp_gt_f32_e64 s[6:7], s66, v77
	v_rsq_f32_e32 v76, v76
	v_pk_mul_f32 v[74:75], v[70:71], s[28:29] op_sel_hi:[1,0]
	v_cndmask_b32_e64 v77, v77, v78, s[6:7]
	v_rsq_f32_e32 v77, v77
	v_cndmask_b32_e64 v71, v71, v75, s[10:11]
	v_cndmask_b32_e64 v70, v70, v74, s[8:9]
	v_pk_mul_f32 v[74:75], v[56:57], v[70:71]
	v_pk_mul_f32 v[56:57], v[76:77], s[28:29] op_sel_hi:[1,0]
	v_pk_mul_f32 v[60:61], v[60:61], v[66:67]
	v_cndmask_b32_e64 v77, v77, v57, s[6:7]
	v_cndmask_b32_e32 v76, v76, v56, vcc
	v_pk_mul_f32 v[62:63], v[62:63], v[68:69]
	v_pk_mul_f32 v[78:79], v[58:59], v[76:77]
	v_cvt_pk_bf16_f32 v56, v60, v61
	v_cvt_pk_bf16_f32 v57, v62, v63
	v_cvt_pk_bf16_f32 v58, v74, v75
	v_cvt_pk_bf16_f32 v59, v78, v79
	v_lshl_add_u64 v[60:61], v[120:121], 0, v[136:137]
	global_store_dwordx4 v[60:61], v[56:59], off nt
	v_pk_mul_f32 v[52:53], v[52:53], v[66:67]
	v_pk_mul_f32 v[54:55], v[54:55], v[68:69]
	v_pk_mul_f32 v[56:57], v[48:49], v[70:71]
	v_pk_mul_f32 v[58:59], v[50:51], v[76:77]
	v_cvt_pk_bf16_f32 v48, v52, v53
	v_cvt_pk_bf16_f32 v49, v54, v55
	v_cvt_pk_bf16_f32 v50, v56, v57
	v_cvt_pk_bf16_f32 v51, v58, v59
	v_lshl_add_u64 v[52:53], v[112:113], 0, v[136:137]
	global_store_dwordx4 v[52:53], v[48:51], off nt
	v_pk_mul_f32 v[44:45], v[44:45], v[66:67]
	v_pk_mul_f32 v[46:47], v[46:47], v[68:69]
	v_pk_mul_f32 v[48:49], v[40:41], v[70:71]
	v_pk_mul_f32 v[50:51], v[42:43], v[76:77]
	v_cvt_pk_bf16_f32 v40, v44, v45
	v_cvt_pk_bf16_f32 v41, v46, v47
	v_cvt_pk_bf16_f32 v42, v48, v49
	v_cvt_pk_bf16_f32 v43, v50, v51
	v_lshl_add_u64 v[44:45], v[104:105], 0, v[136:137]
	global_store_dwordx4 v[44:45], v[40:43], off nt
	v_pk_mul_f32 v[36:37], v[36:37], v[66:67]
	v_pk_mul_f32 v[38:39], v[38:39], v[68:69]
	v_pk_mul_f32 v[40:41], v[32:33], v[70:71]
	v_pk_mul_f32 v[42:43], v[34:35], v[76:77]
	v_cvt_pk_bf16_f32 v32, v36, v37
	v_cvt_pk_bf16_f32 v33, v38, v39
	v_cvt_pk_bf16_f32 v34, v40, v41
	v_cvt_pk_bf16_f32 v35, v42, v43
	v_lshl_add_u64 v[36:37], v[96:97], 0, v[136:137]
	global_store_dwordx4 v[36:37], v[32:35], off nt
	v_pk_mul_f32 v[28:29], v[28:29], v[66:67]
	v_pk_mul_f32 v[30:31], v[30:31], v[68:69]
	v_pk_mul_f32 v[32:33], v[24:25], v[70:71]
	v_pk_mul_f32 v[34:35], v[26:27], v[76:77]
	v_cvt_pk_bf16_f32 v24, v28, v29
	v_cvt_pk_bf16_f32 v25, v30, v31
	v_cvt_pk_bf16_f32 v26, v32, v33
	v_cvt_pk_bf16_f32 v27, v34, v35
	v_lshl_add_u64 v[28:29], v[88:89], 0, v[136:137]
	global_store_dwordx4 v[28:29], v[24:27], off nt
	v_pk_mul_f32 v[20:21], v[20:21], v[66:67]
	v_pk_mul_f32 v[22:23], v[22:23], v[68:69]
	v_pk_mul_f32 v[24:25], v[16:17], v[70:71]
	v_pk_mul_f32 v[26:27], v[18:19], v[76:77]
	v_cvt_pk_bf16_f32 v16, v20, v21
	v_cvt_pk_bf16_f32 v17, v22, v23
	v_cvt_pk_bf16_f32 v18, v24, v25
	v_cvt_pk_bf16_f32 v19, v26, v27
	v_lshl_add_u64 v[20:21], v[80:81], 0, v[136:137]
	global_store_dwordx4 v[20:21], v[16:19], off nt
	v_pk_mul_f32 v[12:13], v[12:13], v[66:67]
	v_pk_mul_f32 v[14:15], v[14:15], v[68:69]
	v_pk_mul_f32 v[16:17], v[8:9], v[70:71]
	v_pk_mul_f32 v[18:19], v[10:11], v[76:77]
	v_cvt_pk_bf16_f32 v8, v12, v13
	v_cvt_pk_bf16_f32 v9, v14, v15
	v_cvt_pk_bf16_f32 v10, v16, v17
	v_cvt_pk_bf16_f32 v11, v18, v19
	v_lshl_add_u64 v[12:13], v[72:73], 0, v[136:137]
	global_store_dwordx4 v[12:13], v[8:11], off nt
	v_pk_mul_f32 v[4:5], v[4:5], v[66:67]
	v_pk_mul_f32 v[6:7], v[6:7], v[68:69]
	v_pk_mul_f32 v[8:9], v[0:1], v[70:71]
	v_pk_mul_f32 v[10:11], v[2:3], v[76:77]
	v_cvt_pk_bf16_f32 v0, v4, v5
	v_cvt_pk_bf16_f32 v1, v6, v7
	v_cvt_pk_bf16_f32 v2, v8, v9
	v_cvt_pk_bf16_f32 v3, v10, v11
	v_lshl_add_u64 v[4:5], v[64:65], 0, v[136:137]
	global_store_dwordx4 v[4:5], v[0:3], off nt
	s_andn2_b64 vcc, exec, s[4:5]
	s_mov_b64 s[4:5], -1
	s_cbranch_vccnz .LBB0_373
	s_andn2_b64 vcc, exec, s[12:13]
	s_cbranch_vccnz .LBB0_372
	s_barrier
	s_branch .LBB0_372

.LBB0_1019:
	v_lshl_add_u32 v152, s14, 8, v146
	s_lshl_b32 s14, s15, 8
	v_ashrrev_i32_e32 v153, 31, v152
	s_ashr_i32 s15, s14, 31
	v_lshlrev_b64 v[154:155], 13, v[152:153]
	v_lshl_add_u64 v[154:155], s[8:9], 0, v[154:155]
	s_lshl_b64 s[14:15], s[14:15], 2
	v_lshl_add_u64 v[154:155], v[154:155], 0, s[14:15]
	v_lshl_add_u64 v[154:155], v[154:155], 0, v[136:137]
	global_store_dwordx4 v[154:155], v[124:127], off nt
	global_store_dwordx4 v[154:155], v[120:123], off offset:16 nt
	global_store_dwordx4 v[154:155], v[108:111], off offset:512 nt
	global_store_dwordx4 v[154:155], v[104:107], off offset:528 nt
	s_nop 1
	v_or_b32_e32 v104, 16, v152
	v_ashrrev_i32_e32 v105, 31, v104
	v_lshlrev_b64 v[104:105], 13, v[104:105]
	v_lshl_add_u64 v[104:105], s[8:9], 0, v[104:105]
	v_lshl_add_u64 v[104:105], v[104:105], 0, s[14:15]
	v_lshl_add_u64 v[104:105], v[104:105], 0, v[136:137]
	global_store_dwordx4 v[104:105], v[116:119], off nt
	global_store_dwordx4 v[104:105], v[112:115], off offset:16 nt
	global_store_dwordx4 v[104:105], v[92:95], off offset:512 nt
	global_store_dwordx4 v[104:105], v[88:91], off offset:528 nt
	s_nop 1
	v_or_b32_e32 v88, 32, v152
	v_ashrrev_i32_e32 v89, 31, v88
	v_lshlrev_b64 v[88:89], 13, v[88:89]
	v_lshl_add_u64 v[88:89], s[8:9], 0, v[88:89]
	v_lshl_add_u64 v[88:89], v[88:89], 0, s[14:15]
	v_lshl_add_u64 v[88:89], v[88:89], 0, v[136:137]
	global_store_dwordx4 v[88:89], v[100:103], off nt
	global_store_dwordx4 v[88:89], v[96:99], off offset:16 nt
	global_store_dwordx4 v[88:89], v[76:79], off offset:512 nt
	global_store_dwordx4 v[88:89], v[72:75], off offset:528 nt
	s_nop 1
	v_or_b32_e32 v72, 48, v152
	v_ashrrev_i32_e32 v73, 31, v72
	v_lshlrev_b64 v[72:73], 13, v[72:73]
	v_lshl_add_u64 v[72:73], s[8:9], 0, v[72:73]
	v_lshl_add_u64 v[72:73], v[72:73], 0, s[14:15]
	v_lshl_add_u64 v[72:73], v[72:73], 0, v[136:137]
	global_store_dwordx4 v[72:73], v[84:87], off nt
	global_store_dwordx4 v[72:73], v[80:83], off offset:16 nt
	global_store_dwordx4 v[72:73], v[68:71], off offset:512 nt
	global_store_dwordx4 v[72:73], v[64:67], off offset:528 nt
	s_nop 1
	v_add_u32_e32 v64, 0x80, v152
	v_ashrrev_i32_e32 v65, 31, v64
	v_lshlrev_b64 v[64:65], 13, v[64:65]
	v_lshl_add_u64 v[64:65], s[8:9], 0, v[64:65]
	v_lshl_add_u64 v[64:65], v[64:65], 0, s[14:15]
	v_lshl_add_u64 v[64:65], v[64:65], 0, v[136:137]
	global_store_dwordx4 v[64:65], v[60:63], off nt
	global_store_dwordx4 v[64:65], v[56:59], off offset:16 nt
	global_store_dwordx4 v[64:65], v[44:47], off offset:512 nt
	global_store_dwordx4 v[64:65], v[40:43], off offset:528 nt
	s_nop 1
	v_add_u32_e32 v40, 0x90, v152
	v_ashrrev_i32_e32 v41, 31, v40
	v_lshlrev_b64 v[40:41], 13, v[40:41]
	v_lshl_add_u64 v[40:41], s[8:9], 0, v[40:41]
	v_lshl_add_u64 v[40:41], v[40:41], 0, s[14:15]
	v_lshl_add_u64 v[40:41], v[40:41], 0, v[136:137]
	global_store_dwordx4 v[40:41], v[52:55], off nt
	global_store_dwordx4 v[40:41], v[48:51], off offset:16 nt
	global_store_dwordx4 v[40:41], v[28:31], off offset:512 nt
	global_store_dwordx4 v[40:41], v[24:27], off offset:528 nt
	s_nop 1
	v_add_u32_e32 v24, 0xa0, v152
	v_ashrrev_i32_e32 v25, 31, v24
	v_lshlrev_b64 v[24:25], 13, v[24:25]
	v_lshl_add_u64 v[24:25], s[8:9], 0, v[24:25]
	v_lshl_add_u64 v[24:25], v[24:25], 0, s[14:15]
	v_lshl_add_u64 v[24:25], v[24:25], 0, v[136:137]
	global_store_dwordx4 v[24:25], v[36:39], off nt
	global_store_dwordx4 v[24:25], v[32:35], off offset:16 nt
	global_store_dwordx4 v[24:25], v[12:15], off offset:512 nt
	global_store_dwordx4 v[24:25], v[8:11], off offset:528 nt
	s_nop 1
	v_add_u32_e32 v8, 0xb0, v152
	v_ashrrev_i32_e32 v9, 31, v8
	v_lshlrev_b64 v[8:9], 13, v[8:9]
	v_lshl_add_u64 v[8:9], s[8:9], 0, v[8:9]
	v_lshl_add_u64 v[8:9], v[8:9], 0, s[14:15]
	v_lshl_add_u64 v[8:9], v[8:9], 0, v[136:137]
	global_store_dwordx4 v[8:9], v[20:23], off nt
	global_store_dwordx4 v[8:9], v[16:19], off offset:16 nt
	global_store_dwordx4 v[8:9], v[4:7], off offset:512 nt
	global_store_dwordx4 v[8:9], v[0:3], off offset:528 nt
	s_andn2_b64 vcc, exec, s[4:5]
	s_mov_b64 s[4:5], -1
	s_cbranch_vccnz .LBB0_1008
	s_andn2_b64 vcc, exec, s[6:7]
	s_cbranch_vccnz .LBB0_1007
	s_barrier
	s_branch .LBB0_1007
